# P8 and P5 residual epilogues software-pipelined (x loads prefetched 2-4 row groups ahead, counted vmcnt) on top of v1
# speedup vs baseline: 1.0001x; 1.0001x over previous
;     template <bool GATE> __device__ __forceinline__ void run(const f32x4 (&acc)[2][2][4][2], const Unit& u, int wr, int wc, int fr, int fq) const {
;     ...
;             for (int m = 0; m < 4; ++m) { const size_t r = (size_t)(row0 + ai * HALF + m * 16); float ss = 0.f;
; #pragma unroll
;                 for (int bj = 0; bj < 2; ++bj) { const int c = col0 + bj * HALF; f32x4 v0 = acc[ai][bj][m][0], v1 = acc[ai][bj][m][1];
;                     if (MODE == EP_INPROJ) { if (gate) { v0 = sigmoid4(v0 + bv[bj][0]); v1 = sigmoid4(v1 + bv[bj][1]); } }
;                     if (MODE == EP_T1 || MODE == EP_MERGE) { f32x4 g0, g1; unpack8(*(const u32x4*)(Gt + r * ldg + c), g0, g1); v0 = v0 * g0; v1 = v1 * g1; }
;                     if (MODE == EP_MERGE) { f32x4 t0, t1; unpack8(*(const u32x4*)(T + r * ldt + c), t0, t1); v0 = v0 + t0; v1 = v1 + t1; }
;                     if (MODE == EP_RELU2) {
; #pragma unroll
;                         for (int i = 0; i < 4; ++i) { const float a = fmaxf(v0[i], 0.f), b = fmaxf(v1[i], 0.f); v0[i] = a * a * rsc[ai][m]; v1[i] = b * b * rsc[ai][m]; } }
;                     if (MODE == EP_RESID_N) { const float* xp = X + r * 2048 + c; float* op = XO + r * 2048 + c;
;                         const f32x4 y0 = *(const f32x4*)xp + v0, y1 = *(const f32x4*)(xp + 4) + v1; *(f32x4*)op = y0; *(f32x4*)(op + 4) = y1;
;                         ss += (y0[0] * y0[0] + y0[1] * y0[1]) + (y0[2] * y0[2] + y0[3] * y0[3]) + (y1[0] * y1[0] + y1[1] * y1[1]) + (y1[2] * y1[2] + y1[3] * y1[3]);
;                         v0 = y0 * bv[bj][0]; v1 = y1 * bv[bj][1]; }
;                     if (MODE == EP_RESID) { const float* xp = X + r * 2048 + c; float* op = XO + r * 2048 + c;
;                         const f32x4 x0 = *(const f32x4*)xp, x1 = *(const f32x4*)(xp + 4); *(f32x4*)op = x0 + v0; *(f32x4*)(op + 4) = x1 + v1; }
;                     else { u32x4 w; w.x = cvt_pk_bf16(v0[0], v0[1]); w.y = cvt_pk_bf16(v0[2], v0[3]); w.z = cvt_pk_bf16(v1[0], v1[1]); w.w = cvt_pk_bf16(v1[2], v1[3]);
;                         *(u32x4*)(O + r * ldc + c) = w; } }
;                 if (MODE == EP_INPROJ) { if (u.pn >= ldt && u.pn < ldt + 8) {
; #pragma unroll
;                     for (int bj = 0; bj < 2; ++bj) { const f32x4 a = acc[ai][bj][m][0], b = acc[ai][bj][m][1];
.LBB0_687:
	v_lshl_add_u32 v158, s22, 8, v164
	v_lshl_or_b32 v154, s21, 8, v166
	v_ashrrev_i32_e32 v159, 31, v158
	v_ashrrev_i32_e32 v155, 31, v154
	v_lshlrev_b64 v[160:161], 13, v[158:159]
	v_lshlrev_b64 v[156:157], 2, v[154:155]
	v_lshl_add_u64 v[162:163], s[36:37], 0, v[160:161]
	v_lshl_add_u64 v[28:29], s[48:49], 0, v[156:157]
	v_lshl_add_u64 v[162:163], v[162:163], 0, v[156:157]
	global_load_dwordx4 v[48:51], v[28:29], off offset:16
	global_load_dwordx4 v[52:55], v[28:29], off
	global_load_dwordx4 v[24:27], v[28:29], off offset:528
	s_nop 0
	global_load_dwordx4 v[28:31], v[28:29], off offset:512
	v_mov_b32_e32 v226, v162
	v_mov_b32_e32 v227, v163
	global_load_dwordx4 v[176:179], v[226:227], off offset:16
	global_load_dwordx4 v[180:183], v[226:227], off
	global_load_dwordx4 v[184:187], v[226:227], off offset:528
	global_load_dwordx4 v[188:191], v[226:227], off offset:512
	v_add_co_u32_e32 v200, vcc, 0x20000, v226
	s_nop 1
	v_addc_co_u32_e32 v201, vcc, 0, v227, vcc
	global_load_dwordx4 v[210:213], v[200:201], off offset:16
	global_load_dwordx4 v[214:217], v[200:201], off
	global_load_dwordx4 v[218:221], v[200:201], off offset:528
	global_load_dwordx4 v[222:225], v[200:201], off offset:512
	s_nop 0
	v_lshl_add_u64 v[160:161], s[66:67], 0, v[160:161]
	v_lshl_add_u64 v[160:161], v[160:161], 0, v[156:157]
	s_waitcnt vmcnt(7)
	v_pk_add_f32 v[136:137], v[136:137], v[176:177]
	s_waitcnt vmcnt(6)
	v_pk_add_f32 v[142:143], v[142:143], v[182:183]
	v_pk_add_f32 v[140:141], v[140:141], v[180:181]
	v_mul_f32_e32 v169, v143, v143
	v_mul_f32_e32 v168, v141, v141
	v_fmac_f32_e32 v168, v140, v140
	v_fmac_f32_e32 v169, v142, v142
	v_add_f32_e32 v168, v168, v169
	v_mul_f32_e32 v169, v137, v137
	v_pk_add_f32 v[138:139], v[138:139], v[178:179]
	v_fmac_f32_e32 v169, v136, v136
	v_add_f32_e32 v168, v168, v169
	v_mul_f32_e32 v169, v139, v139
	global_store_dwordx4 v[160:161], v[140:143], off
	global_store_dwordx4 v[160:161], v[136:139], off offset:16
	v_fmac_f32_e32 v169, v138, v138
	v_pk_mul_f32 v[140:141], v[52:53], v[140:141]
	v_add_f32_e32 v170, v169, v168
	v_pk_mul_f32 v[168:169], v[50:51], v[138:139]
	v_pk_mul_f32 v[138:139], v[48:49], v[136:137]
	v_cvt_pk_bf16_f32 v136, v140, v141
	v_lshlrev_b64 v[140:141], 12, v[158:159]
	v_lshl_add_u64 v[140:141], s[10:11], 0, v[140:141]
	v_pk_mul_f32 v[142:143], v[54:55], v[142:143]
	s_nop 0
	v_cvt_pk_bf16_f32 v137, v142, v143
	v_cvt_pk_bf16_f32 v138, v138, v139
	v_cvt_pk_bf16_f32 v139, v168, v169
	v_lshl_add_u64 v[168:169], v[154:155], 1, v[140:141]
	global_store_dwordx4 v[168:169], v[136:139], off
	s_nop 0
	s_waitcnt vmcnt(8)
	v_pk_add_f32 v[128:129], v[128:129], v[184:185]
	s_waitcnt vmcnt(7)
	v_pk_add_f32 v[134:135], v[134:135], v[190:191]
	v_pk_add_f32 v[132:133], v[132:133], v[188:189]
	v_mul_f32_e32 v137, v135, v135
	v_mul_f32_e32 v136, v133, v133
	v_fmac_f32_e32 v136, v132, v132
	v_fmac_f32_e32 v137, v134, v134
	v_add_f32_e32 v136, v136, v137
	v_mul_f32_e32 v137, v129, v129
	v_pk_add_f32 v[130:131], v[130:131], v[186:187]
	v_add_co_u32_e32 v200, vcc, 0x40000, v226
	s_nop 1
	v_addc_co_u32_e32 v201, vcc, 0, v227, vcc
	global_load_dwordx4 v[176:179], v[200:201], off offset:16
	global_load_dwordx4 v[180:183], v[200:201], off
	global_load_dwordx4 v[184:187], v[200:201], off offset:528
	global_load_dwordx4 v[188:191], v[200:201], off offset:512
	v_fmac_f32_e32 v137, v128, v128
	v_add_f32_e32 v136, v136, v137
	v_mul_f32_e32 v137, v131, v131
	v_fmac_f32_e32 v137, v130, v130
	v_add_f32_e32 v136, v137, v136
	global_store_dwordx4 v[160:161], v[132:135], off offset:512
	global_store_dwordx4 v[160:161], v[128:131], off offset:528
	v_add_f32_e32 v138, v170, v136
	v_pk_mul_f32 v[132:133], v[28:29], v[132:133]
	v_pk_mul_f32 v[136:137], v[26:27], v[130:131]
	v_pk_mul_f32 v[130:131], v[24:25], v[128:129]
	v_cvt_pk_bf16_f32 v128, v132, v133
	v_pk_mul_f32 v[134:135], v[30:31], v[134:135]
	s_nop 0
	v_cvt_pk_bf16_f32 v129, v134, v135
	v_cvt_pk_bf16_f32 v130, v130, v131
	v_cvt_pk_bf16_f32 v131, v136, v137
	global_store_dwordx4 v[168:169], v[128:131], off offset:256
	ds_swizzle_b32 v128, v138 offset:swizzle(SWAP,16)
	s_waitcnt lgkmcnt(0)
	v_add_f32_e32 v128, v138, v128
	v_mov_b32_e32 v129, v128
	s_nop 1
	v_permlane32_swap_b32_e32 v128, v129
	s_and_saveexec_b64 s[14:15], s[42:43]
	v_lshl_add_u64 v[130:131], v[158:159], 2, s[12:13]
	v_add_f32_e32 v128, v128, v129
	global_atomic_add_f32 v[130:131], v128, off
;     template <bool GATE> __device__ __forceinline__ void run(const f32x4 (&acc)[2][2][4][2], const Unit& u, int wr, int wc, int fr, int fq) const {
;     ...
;             for (int m = 0; m < 4; ++m) { const size_t r = (size_t)(row0 + ai * HALF + m * 16); float ss = 0.f;
; #pragma unroll
;                 for (int bj = 0; bj < 2; ++bj) { const int c = col0 + bj * HALF; f32x4 v0 = acc[ai][bj][m][0], v1 = acc[ai][bj][m][1];
;                     if (MODE == EP_INPROJ) { if (gate) { v0 = sigmoid4(v0 + bv[bj][0]); v1 = sigmoid4(v1 + bv[bj][1]); } }
;                     if (MODE == EP_T1 || MODE == EP_MERGE) { f32x4 g0, g1; unpack8(*(const u32x4*)(Gt + r * ldg + c), g0, g1); v0 = v0 * g0; v1 = v1 * g1; }
;                     if (MODE == EP_MERGE) { f32x4 t0, t1; unpack8(*(const u32x4*)(T + r * ldt + c), t0, t1); v0 = v0 + t0; v1 = v1 + t1; }
;                     if (MODE == EP_RELU2) {
; #pragma unroll
;                         for (int i = 0; i < 4; ++i) { const float a = fmaxf(v0[i], 0.f), b = fmaxf(v1[i], 0.f); v0[i] = a * a * rsc[ai][m]; v1[i] = b * b * rsc[ai][m]; } }
;                     if (MODE == EP_RESID_N) { const float* xp = X + r * 2048 + c; float* op = XO + r * 2048 + c;
;                         const f32x4 y0 = *(const f32x4*)xp + v0, y1 = *(const f32x4*)(xp + 4) + v1; *(f32x4*)op = y0; *(f32x4*)(op + 4) = y1;
;                         ss += (y0[0] * y0[0] + y0[1] * y0[1]) + (y0[2] * y0[2] + y0[3] * y0[3]) + (y1[0] * y1[0] + y1[1] * y1[1]) + (y1[2] * y1[2] + y1[3] * y1[3]);
;                         v0 = y0 * bv[bj][0]; v1 = y1 * bv[bj][1]; }
;                     if (MODE == EP_RESID) { const float* xp = X + r * 2048 + c; float* op = XO + r * 2048 + c;
;                         const f32x4 x0 = *(const f32x4*)xp, x1 = *(const f32x4*)(xp + 4); *(f32x4*)op = x0 + v0; *(f32x4*)(op + 4) = x1 + v1; }
;                     else { u32x4 w; w.x = cvt_pk_bf16(v0[0], v0[1]); w.y = cvt_pk_bf16(v0[2], v0[3]); w.z = cvt_pk_bf16(v1[0], v1[1]); w.w = cvt_pk_bf16(v1[2], v1[3]);
;                         *(u32x4*)(O + r * ldc + c) = w; } }
;                 if (MODE == EP_INPROJ) { if (u.pn >= ldt && u.pn < ldt + 8) {
; #pragma unroll
;                     for (int bj = 0; bj < 2; ++bj) { const f32x4 a = acc[ai][bj][m][0], b = acc[ai][bj][m][1];
.LBB0_689:
	s_or_b64 exec, exec, s[14:15]
	v_or_b32_e32 v128, 16, v158
	v_ashrrev_i32_e32 v129, 31, v128
	v_lshlrev_b64 v[130:131], 13, v[128:129]
	v_lshl_add_u64 v[132:133], s[36:37], 0, v[130:131]
	v_lshl_add_u64 v[140:141], v[132:133], 0, v[156:157]
	v_lshl_add_u64 v[130:131], s[66:67], 0, v[130:131]
	v_lshl_add_u64 v[130:131], v[130:131], 0, v[156:157]
	s_waitcnt vmcnt(14)
	v_pk_add_f32 v[120:121], v[120:121], v[210:211]
	s_waitcnt vmcnt(13)
	v_pk_add_f32 v[126:127], v[126:127], v[216:217]
	v_pk_add_f32 v[124:125], v[124:125], v[214:215]
	v_mul_f32_e32 v133, v127, v127
	v_mul_f32_e32 v132, v125, v125
	v_fmac_f32_e32 v132, v124, v124
	v_fmac_f32_e32 v133, v126, v126
	v_add_f32_e32 v132, v132, v133
	v_mul_f32_e32 v133, v121, v121
	v_pk_add_f32 v[122:123], v[122:123], v[212:213]
	v_fmac_f32_e32 v133, v120, v120
	v_add_f32_e32 v132, v132, v133
	v_mul_f32_e32 v133, v123, v123
	global_store_dwordx4 v[130:131], v[124:127], off
	global_store_dwordx4 v[130:131], v[120:123], off offset:16
	v_fmac_f32_e32 v133, v122, v122
	v_pk_mul_f32 v[124:125], v[52:53], v[124:125]
	v_add_f32_e32 v134, v133, v132
	v_pk_mul_f32 v[132:133], v[50:51], v[122:123]
	v_pk_mul_f32 v[122:123], v[48:49], v[120:121]
	v_cvt_pk_bf16_f32 v120, v124, v125
	v_lshlrev_b64 v[124:125], 12, v[128:129]
	v_lshl_add_u64 v[124:125], s[10:11], 0, v[124:125]
	v_pk_mul_f32 v[126:127], v[54:55], v[126:127]
	s_nop 0
	v_cvt_pk_bf16_f32 v121, v126, v127
	v_cvt_pk_bf16_f32 v122, v122, v123
	v_cvt_pk_bf16_f32 v123, v132, v133
	v_lshl_add_u64 v[132:133], v[154:155], 1, v[124:125]
	global_store_dwordx4 v[132:133], v[120:123], off
	s_nop 0
	s_waitcnt vmcnt(15)
	v_pk_add_f32 v[112:113], v[112:113], v[218:219]
	s_waitcnt vmcnt(14)
	v_pk_add_f32 v[118:119], v[118:119], v[224:225]
	v_pk_add_f32 v[116:117], v[116:117], v[222:223]
	v_mul_f32_e32 v121, v119, v119
	v_mul_f32_e32 v120, v117, v117
	v_fmac_f32_e32 v120, v116, v116
	v_fmac_f32_e32 v121, v118, v118
	v_add_f32_e32 v120, v120, v121
	v_mul_f32_e32 v121, v113, v113
	v_pk_add_f32 v[114:115], v[114:115], v[220:221]
	v_add_co_u32_e32 v200, vcc, 0x60000, v226
	s_nop 1
	v_addc_co_u32_e32 v201, vcc, 0, v227, vcc
	global_load_dwordx4 v[210:213], v[200:201], off offset:16
	global_load_dwordx4 v[214:217], v[200:201], off
	global_load_dwordx4 v[218:221], v[200:201], off offset:528
	global_load_dwordx4 v[222:225], v[200:201], off offset:512
	v_fmac_f32_e32 v121, v112, v112
	v_add_f32_e32 v120, v120, v121
	v_mul_f32_e32 v121, v115, v115
	v_fmac_f32_e32 v121, v114, v114
	v_add_f32_e32 v120, v121, v120
	global_store_dwordx4 v[130:131], v[116:119], off offset:512
	global_store_dwordx4 v[130:131], v[112:115], off offset:528
	v_add_f32_e32 v122, v134, v120
	v_pk_mul_f32 v[116:117], v[28:29], v[116:117]
	v_pk_mul_f32 v[120:121], v[26:27], v[114:115]
	v_pk_mul_f32 v[114:115], v[24:25], v[112:113]
	v_cvt_pk_bf16_f32 v112, v116, v117
	v_pk_mul_f32 v[118:119], v[30:31], v[118:119]
	s_nop 0
	v_cvt_pk_bf16_f32 v113, v118, v119
	v_cvt_pk_bf16_f32 v114, v114, v115
	v_cvt_pk_bf16_f32 v115, v120, v121
	global_store_dwordx4 v[132:133], v[112:115], off offset:256
	ds_swizzle_b32 v112, v122 offset:swizzle(SWAP,16)
	s_waitcnt lgkmcnt(0)
	v_add_f32_e32 v112, v122, v112
	v_mov_b32_e32 v113, v112
	s_nop 1
	v_permlane32_swap_b32_e32 v112, v113
	s_and_saveexec_b64 s[14:15], s[42:43]
	v_lshl_add_u64 v[114:115], v[128:129], 2, s[12:13]
	v_add_f32_e32 v112, v112, v113
	global_atomic_add_f32 v[114:115], v112, off
.LBB0_691:
	s_or_b64 exec, exec, s[14:15]
	v_or_b32_e32 v112, 32, v158
	v_ashrrev_i32_e32 v113, 31, v112
	v_lshlrev_b64 v[114:115], 13, v[112:113]
	v_lshl_add_u64 v[116:117], s[36:37], 0, v[114:115]
	v_lshl_add_u64 v[116:117], v[116:117], 0, v[156:157]
	v_lshl_add_u64 v[114:115], s[66:67], 0, v[114:115]
	v_lshl_add_u64 v[114:115], v[114:115], 0, v[156:157]
	s_waitcnt vmcnt(18)
	v_pk_add_f32 v[104:105], v[104:105], v[176:177]
	s_waitcnt vmcnt(17)
	v_pk_add_f32 v[110:111], v[110:111], v[182:183]
	v_pk_add_f32 v[108:109], v[108:109], v[180:181]
	v_mul_f32_e32 v119, v111, v111
	v_mul_f32_e32 v118, v109, v109
	v_fmac_f32_e32 v118, v108, v108
	v_fmac_f32_e32 v119, v110, v110
	v_add_f32_e32 v118, v118, v119
	v_mul_f32_e32 v119, v105, v105
	v_pk_add_f32 v[106:107], v[106:107], v[178:179]
	v_fmac_f32_e32 v119, v104, v104
	v_add_f32_e32 v118, v118, v119
	v_mul_f32_e32 v119, v107, v107
	global_store_dwordx4 v[114:115], v[108:111], off
	global_store_dwordx4 v[114:115], v[104:107], off offset:16
	v_fmac_f32_e32 v119, v106, v106
	v_pk_mul_f32 v[108:109], v[52:53], v[108:109]
	v_add_f32_e32 v120, v119, v118
	v_pk_mul_f32 v[118:119], v[50:51], v[106:107]
	v_pk_mul_f32 v[106:107], v[48:49], v[104:105]
	v_cvt_pk_bf16_f32 v104, v108, v109
	v_lshlrev_b64 v[108:109], 12, v[112:113]
	v_lshl_add_u64 v[108:109], s[10:11], 0, v[108:109]
	v_pk_mul_f32 v[110:111], v[54:55], v[110:111]
	s_nop 0
	v_cvt_pk_bf16_f32 v105, v110, v111
	v_cvt_pk_bf16_f32 v106, v106, v107
	v_cvt_pk_bf16_f32 v107, v118, v119
	v_lshl_add_u64 v[118:119], v[154:155], 1, v[108:109]
	global_store_dwordx4 v[118:119], v[104:107], off
	s_nop 0
	s_waitcnt vmcnt(19)
	v_pk_add_f32 v[96:97], v[96:97], v[184:185]
	s_waitcnt vmcnt(18)
	v_pk_add_f32 v[102:103], v[102:103], v[190:191]
	v_pk_add_f32 v[100:101], v[100:101], v[188:189]
	v_mul_f32_e32 v105, v103, v103
	v_mul_f32_e32 v104, v101, v101
	v_fmac_f32_e32 v104, v100, v100
	v_fmac_f32_e32 v105, v102, v102
	v_add_f32_e32 v104, v104, v105
	v_mul_f32_e32 v105, v97, v97
	v_pk_add_f32 v[98:99], v[98:99], v[186:187]
	v_add_co_u32_e32 v200, vcc, 0x100000, v226
	s_nop 1
	v_addc_co_u32_e32 v201, vcc, 0, v227, vcc
	global_load_dwordx4 v[176:179], v[200:201], off offset:16
	global_load_dwordx4 v[180:183], v[200:201], off
	global_load_dwordx4 v[184:187], v[200:201], off offset:528
	global_load_dwordx4 v[188:191], v[200:201], off offset:512
	v_fmac_f32_e32 v105, v96, v96
	v_add_f32_e32 v104, v104, v105
	v_mul_f32_e32 v105, v99, v99
	v_fmac_f32_e32 v105, v98, v98
	v_add_f32_e32 v104, v105, v104
	global_store_dwordx4 v[114:115], v[100:103], off offset:512
	global_store_dwordx4 v[114:115], v[96:99], off offset:528
	v_add_f32_e32 v106, v120, v104
	v_pk_mul_f32 v[100:101], v[28:29], v[100:101]
	v_pk_mul_f32 v[104:105], v[26:27], v[98:99]
	v_pk_mul_f32 v[98:99], v[24:25], v[96:97]
	v_cvt_pk_bf16_f32 v96, v100, v101
	v_pk_mul_f32 v[102:103], v[30:31], v[102:103]
	s_nop 0
	v_cvt_pk_bf16_f32 v97, v102, v103
	v_cvt_pk_bf16_f32 v98, v98, v99
	v_cvt_pk_bf16_f32 v99, v104, v105
	global_store_dwordx4 v[118:119], v[96:99], off offset:256
	ds_swizzle_b32 v96, v106 offset:swizzle(SWAP,16)
	s_waitcnt lgkmcnt(0)
	v_add_f32_e32 v96, v106, v96
	v_mov_b32_e32 v97, v96
	s_nop 1
	v_permlane32_swap_b32_e32 v96, v97
	s_and_saveexec_b64 s[14:15], s[42:43]
	v_lshl_add_u64 v[98:99], v[112:113], 2, s[12:13]
	v_add_f32_e32 v96, v96, v97
	global_atomic_add_f32 v[98:99], v96, off
;     template <bool GATE> __device__ __forceinline__ void run(const f32x4 (&acc)[2][2][4][2], const Unit& u, int wr, int wc, int fr, int fq) const {
;     ...
;             for (int m = 0; m < 4; ++m) { const size_t r = (size_t)(row0 + ai * HALF + m * 16); float ss = 0.f;
; #pragma unroll
;                 for (int bj = 0; bj < 2; ++bj) { const int c = col0 + bj * HALF; f32x4 v0 = acc[ai][bj][m][0], v1 = acc[ai][bj][m][1];
;                     if (MODE == EP_INPROJ) { if (gate) { v0 = sigmoid4(v0 + bv[bj][0]); v1 = sigmoid4(v1 + bv[bj][1]); } }
;                     if (MODE == EP_T1 || MODE == EP_MERGE) { f32x4 g0, g1; unpack8(*(const u32x4*)(Gt + r * ldg + c), g0, g1); v0 = v0 * g0; v1 = v1 * g1; }
;                     if (MODE == EP_MERGE) { f32x4 t0, t1; unpack8(*(const u32x4*)(T + r * ldt + c), t0, t1); v0 = v0 + t0; v1 = v1 + t1; }
;                     if (MODE == EP_RELU2) {
; #pragma unroll
;                         for (int i = 0; i < 4; ++i) { const float a = fmaxf(v0[i], 0.f), b = fmaxf(v1[i], 0.f); v0[i] = a * a * rsc[ai][m]; v1[i] = b * b * rsc[ai][m]; } }
;                     if (MODE == EP_RESID_N) { const float* xp = X + r * 2048 + c; float* op = XO + r * 2048 + c;
;                         const f32x4 y0 = *(const f32x4*)xp + v0, y1 = *(const f32x4*)(xp + 4) + v1; *(f32x4*)op = y0; *(f32x4*)(op + 4) = y1;
;                         ss += (y0[0] * y0[0] + y0[1] * y0[1]) + (y0[2] * y0[2] + y0[3] * y0[3]) + (y1[0] * y1[0] + y1[1] * y1[1]) + (y1[2] * y1[2] + y1[3] * y1[3]);
;                         v0 = y0 * bv[bj][0]; v1 = y1 * bv[bj][1]; }
;                     if (MODE == EP_RESID) { const float* xp = X + r * 2048 + c; float* op = XO + r * 2048 + c;
;                         const f32x4 x0 = *(const f32x4*)xp, x1 = *(const f32x4*)(xp + 4); *(f32x4*)op = x0 + v0; *(f32x4*)(op + 4) = x1 + v1; }
;                     else { u32x4 w; w.x = cvt_pk_bf16(v0[0], v0[1]); w.y = cvt_pk_bf16(v0[2], v0[3]); w.z = cvt_pk_bf16(v1[0], v1[1]); w.w = cvt_pk_bf16(v1[2], v1[3]);
;                         *(u32x4*)(O + r * ldc + c) = w; } }
;                 if (MODE == EP_INPROJ) { if (u.pn >= ldt && u.pn < ldt + 8) {
; #pragma unroll
;                     for (int bj = 0; bj < 2; ++bj) { const f32x4 a = acc[ai][bj][m][0], b = acc[ai][bj][m][1];
.LBB0_693:
	s_or_b64 exec, exec, s[14:15]
	v_or_b32_e32 v96, 48, v158
	v_ashrrev_i32_e32 v97, 31, v96
	v_lshlrev_b64 v[98:99], 13, v[96:97]
	v_lshl_add_u64 v[100:101], s[36:37], 0, v[98:99]
	v_lshl_add_u64 v[108:109], v[100:101], 0, v[156:157]
	v_lshl_add_u64 v[98:99], s[66:67], 0, v[98:99]
	v_lshl_add_u64 v[98:99], v[98:99], 0, v[156:157]
	s_waitcnt vmcnt(18)
	v_pk_add_f32 v[88:89], v[88:89], v[210:211]
	s_waitcnt vmcnt(17)
	v_pk_add_f32 v[94:95], v[94:95], v[216:217]
	v_pk_add_f32 v[92:93], v[92:93], v[214:215]
	v_mul_f32_e32 v101, v95, v95
	v_mul_f32_e32 v100, v93, v93
	v_fmac_f32_e32 v100, v92, v92
	v_fmac_f32_e32 v101, v94, v94
	v_add_f32_e32 v100, v100, v101
	v_mul_f32_e32 v101, v89, v89
	v_pk_add_f32 v[90:91], v[90:91], v[212:213]
	v_fmac_f32_e32 v101, v88, v88
	v_add_f32_e32 v100, v100, v101
	v_mul_f32_e32 v101, v91, v91
	global_store_dwordx4 v[98:99], v[92:95], off
	global_store_dwordx4 v[98:99], v[88:91], off offset:16
	v_fmac_f32_e32 v101, v90, v90
	v_pk_mul_f32 v[92:93], v[52:53], v[92:93]
	v_add_f32_e32 v102, v101, v100
	v_pk_mul_f32 v[100:101], v[50:51], v[90:91]
	v_pk_mul_f32 v[90:91], v[48:49], v[88:89]
	v_cvt_pk_bf16_f32 v88, v92, v93
	v_lshlrev_b64 v[92:93], 12, v[96:97]
	v_lshl_add_u64 v[92:93], s[10:11], 0, v[92:93]
	v_pk_mul_f32 v[94:95], v[54:55], v[94:95]
	s_nop 0
	v_cvt_pk_bf16_f32 v89, v94, v95
	v_cvt_pk_bf16_f32 v90, v90, v91
	v_cvt_pk_bf16_f32 v91, v100, v101
	v_lshl_add_u64 v[100:101], v[154:155], 1, v[92:93]
	global_store_dwordx4 v[100:101], v[88:91], off
	s_nop 0
	s_waitcnt vmcnt(19)
	v_pk_add_f32 v[80:81], v[80:81], v[218:219]
	s_waitcnt vmcnt(18)
	v_pk_add_f32 v[86:87], v[86:87], v[224:225]
	v_pk_add_f32 v[84:85], v[84:85], v[222:223]
	v_mul_f32_e32 v89, v87, v87
	v_mul_f32_e32 v88, v85, v85
	v_fmac_f32_e32 v88, v84, v84
	v_fmac_f32_e32 v89, v86, v86
	v_add_f32_e32 v88, v88, v89
	v_mul_f32_e32 v89, v81, v81
	v_pk_add_f32 v[82:83], v[82:83], v[220:221]
	v_add_co_u32_e32 v200, vcc, 0x120000, v226
	s_nop 1
	v_addc_co_u32_e32 v201, vcc, 0, v227, vcc
	global_load_dwordx4 v[210:213], v[200:201], off offset:16
	global_load_dwordx4 v[214:217], v[200:201], off
	global_load_dwordx4 v[218:221], v[200:201], off offset:528
	global_load_dwordx4 v[222:225], v[200:201], off offset:512
	v_fmac_f32_e32 v89, v80, v80
	v_add_f32_e32 v88, v88, v89
	v_mul_f32_e32 v89, v83, v83
	v_fmac_f32_e32 v89, v82, v82
	v_add_f32_e32 v88, v89, v88
	global_store_dwordx4 v[98:99], v[84:87], off offset:512
	global_store_dwordx4 v[98:99], v[80:83], off offset:528
	v_add_f32_e32 v90, v102, v88
	v_pk_mul_f32 v[84:85], v[28:29], v[84:85]
	v_pk_mul_f32 v[88:89], v[26:27], v[82:83]
	v_pk_mul_f32 v[82:83], v[24:25], v[80:81]
	v_cvt_pk_bf16_f32 v80, v84, v85
	v_pk_mul_f32 v[86:87], v[30:31], v[86:87]
	s_nop 0
	v_cvt_pk_bf16_f32 v81, v86, v87
	v_cvt_pk_bf16_f32 v82, v82, v83
	v_cvt_pk_bf16_f32 v83, v88, v89
	global_store_dwordx4 v[100:101], v[80:83], off offset:256
	ds_swizzle_b32 v80, v90 offset:swizzle(SWAP,16)
	s_waitcnt lgkmcnt(0)
	v_add_f32_e32 v80, v90, v80
	v_mov_b32_e32 v81, v80
	s_nop 1
	v_permlane32_swap_b32_e32 v80, v81
	s_and_saveexec_b64 s[14:15], s[42:43]
	v_lshl_add_u64 v[82:83], v[96:97], 2, s[12:13]
	v_add_f32_e32 v80, v80, v81
	global_atomic_add_f32 v[82:83], v80, off
.LBB0_695:
	s_or_b64 exec, exec, s[14:15]
	v_add_u32_e32 v80, 0x80, v158
	v_ashrrev_i32_e32 v81, 31, v80
	v_lshlrev_b64 v[82:83], 13, v[80:81]
	v_lshl_add_u64 v[84:85], s[36:37], 0, v[82:83]
	v_lshl_add_u64 v[84:85], v[84:85], 0, v[156:157]
	v_lshl_add_u64 v[82:83], s[66:67], 0, v[82:83]
	v_lshl_add_u64 v[82:83], v[82:83], 0, v[156:157]
	s_waitcnt vmcnt(18)
	v_pk_add_f32 v[72:73], v[72:73], v[176:177]
	s_waitcnt vmcnt(17)
	v_pk_add_f32 v[78:79], v[78:79], v[182:183]
	v_pk_add_f32 v[76:77], v[76:77], v[180:181]
	v_mul_f32_e32 v87, v79, v79
	v_mul_f32_e32 v86, v77, v77
	v_fmac_f32_e32 v86, v76, v76
	v_fmac_f32_e32 v87, v78, v78
	v_add_f32_e32 v86, v86, v87
	v_mul_f32_e32 v87, v73, v73
	v_pk_add_f32 v[74:75], v[74:75], v[178:179]
	v_fmac_f32_e32 v87, v72, v72
	v_add_f32_e32 v86, v86, v87
	v_mul_f32_e32 v87, v75, v75
	global_store_dwordx4 v[82:83], v[76:79], off
	global_store_dwordx4 v[82:83], v[72:75], off offset:16
	v_fmac_f32_e32 v87, v74, v74
	v_pk_mul_f32 v[76:77], v[52:53], v[76:77]
	v_add_f32_e32 v88, v87, v86
	v_pk_mul_f32 v[86:87], v[50:51], v[74:75]
	v_pk_mul_f32 v[74:75], v[48:49], v[72:73]
	v_cvt_pk_bf16_f32 v72, v76, v77
	v_lshlrev_b64 v[76:77], 12, v[80:81]
	v_lshl_add_u64 v[76:77], s[10:11], 0, v[76:77]
	v_pk_mul_f32 v[78:79], v[54:55], v[78:79]
	s_nop 0
	v_cvt_pk_bf16_f32 v73, v78, v79
	v_cvt_pk_bf16_f32 v74, v74, v75
	v_cvt_pk_bf16_f32 v75, v86, v87
	v_lshl_add_u64 v[86:87], v[154:155], 1, v[76:77]
	global_store_dwordx4 v[86:87], v[72:75], off
	s_nop 0
	s_waitcnt vmcnt(19)
	v_pk_add_f32 v[64:65], v[64:65], v[184:185]
	s_waitcnt vmcnt(18)
	v_pk_add_f32 v[70:71], v[70:71], v[190:191]
	v_pk_add_f32 v[68:69], v[68:69], v[188:189]
	v_mul_f32_e32 v73, v71, v71
	v_mul_f32_e32 v72, v69, v69
	v_fmac_f32_e32 v72, v68, v68
	v_fmac_f32_e32 v73, v70, v70
	v_add_f32_e32 v72, v72, v73
	v_mul_f32_e32 v73, v65, v65
	v_pk_add_f32 v[66:67], v[66:67], v[186:187]
	v_add_co_u32_e32 v200, vcc, 0x140000, v226
	s_nop 1
	v_addc_co_u32_e32 v201, vcc, 0, v227, vcc
	global_load_dwordx4 v[176:179], v[200:201], off offset:16
	global_load_dwordx4 v[180:183], v[200:201], off
	global_load_dwordx4 v[184:187], v[200:201], off offset:528
	global_load_dwordx4 v[188:191], v[200:201], off offset:512
	v_fmac_f32_e32 v73, v64, v64
	v_add_f32_e32 v72, v72, v73
	v_mul_f32_e32 v73, v67, v67
	v_fmac_f32_e32 v73, v66, v66
	v_add_f32_e32 v72, v73, v72
	global_store_dwordx4 v[82:83], v[68:71], off offset:512
	global_store_dwordx4 v[82:83], v[64:67], off offset:528
	v_add_f32_e32 v74, v88, v72
	v_pk_mul_f32 v[68:69], v[28:29], v[68:69]
	v_pk_mul_f32 v[72:73], v[26:27], v[66:67]
	v_pk_mul_f32 v[66:67], v[24:25], v[64:65]
	v_cvt_pk_bf16_f32 v64, v68, v69
	v_pk_mul_f32 v[70:71], v[30:31], v[70:71]
	s_nop 0
	v_cvt_pk_bf16_f32 v65, v70, v71
	v_cvt_pk_bf16_f32 v66, v66, v67
	v_cvt_pk_bf16_f32 v67, v72, v73
	global_store_dwordx4 v[86:87], v[64:67], off offset:256
	ds_swizzle_b32 v64, v74 offset:swizzle(SWAP,16)
	s_waitcnt lgkmcnt(0)
	v_add_f32_e32 v64, v74, v64
	v_mov_b32_e32 v65, v64
	s_nop 1
	v_permlane32_swap_b32_e32 v64, v65
	s_and_saveexec_b64 s[14:15], s[42:43]
	v_lshl_add_u64 v[66:67], v[80:81], 2, s[12:13]
	v_add_f32_e32 v64, v64, v65
	global_atomic_add_f32 v[66:67], v64, off
;     template <bool GATE> __device__ __forceinline__ void run(const f32x4 (&acc)[2][2][4][2], const Unit& u, int wr, int wc, int fr, int fq) const {
;     ...
;             for (int m = 0; m < 4; ++m) { const size_t r = (size_t)(row0 + ai * HALF + m * 16); float ss = 0.f;
; #pragma unroll
;                 for (int bj = 0; bj < 2; ++bj) { const int c = col0 + bj * HALF; f32x4 v0 = acc[ai][bj][m][0], v1 = acc[ai][bj][m][1];
;                     if (MODE == EP_INPROJ) { if (gate) { v0 = sigmoid4(v0 + bv[bj][0]); v1 = sigmoid4(v1 + bv[bj][1]); } }
;                     if (MODE == EP_T1 || MODE == EP_MERGE) { f32x4 g0, g1; unpack8(*(const u32x4*)(Gt + r * ldg + c), g0, g1); v0 = v0 * g0; v1 = v1 * g1; }
;                     if (MODE == EP_MERGE) { f32x4 t0, t1; unpack8(*(const u32x4*)(T + r * ldt + c), t0, t1); v0 = v0 + t0; v1 = v1 + t1; }
;                     if (MODE == EP_RELU2) {
; #pragma unroll
;                         for (int i = 0; i < 4; ++i) { const float a = fmaxf(v0[i], 0.f), b = fmaxf(v1[i], 0.f); v0[i] = a * a * rsc[ai][m]; v1[i] = b * b * rsc[ai][m]; } }
;                     if (MODE == EP_RESID_N) { const float* xp = X + r * 2048 + c; float* op = XO + r * 2048 + c;
;                         const f32x4 y0 = *(const f32x4*)xp + v0, y1 = *(const f32x4*)(xp + 4) + v1; *(f32x4*)op = y0; *(f32x4*)(op + 4) = y1;
;                         ss += (y0[0] * y0[0] + y0[1] * y0[1]) + (y0[2] * y0[2] + y0[3] * y0[3]) + (y1[0] * y1[0] + y1[1] * y1[1]) + (y1[2] * y1[2] + y1[3] * y1[3]);
;                         v0 = y0 * bv[bj][0]; v1 = y1 * bv[bj][1]; }
;                     if (MODE == EP_RESID) { const float* xp = X + r * 2048 + c; float* op = XO + r * 2048 + c;
;                         const f32x4 x0 = *(const f32x4*)xp, x1 = *(const f32x4*)(xp + 4); *(f32x4*)op = x0 + v0; *(f32x4*)(op + 4) = x1 + v1; }
;                     else { u32x4 w; w.x = cvt_pk_bf16(v0[0], v0[1]); w.y = cvt_pk_bf16(v0[2], v0[3]); w.z = cvt_pk_bf16(v1[0], v1[1]); w.w = cvt_pk_bf16(v1[2], v1[3]);
;                         *(u32x4*)(O + r * ldc + c) = w; } }
;                 if (MODE == EP_INPROJ) { if (u.pn >= ldt && u.pn < ldt + 8) {
; #pragma unroll
;                     for (int bj = 0; bj < 2; ++bj) { const f32x4 a = acc[ai][bj][m][0], b = acc[ai][bj][m][1];
.LBB0_697:
	s_or_b64 exec, exec, s[14:15]
	v_add_u32_e32 v64, 0x90, v158
	v_ashrrev_i32_e32 v65, 31, v64
	v_lshlrev_b64 v[66:67], 13, v[64:65]
	v_lshl_add_u64 v[68:69], s[36:37], 0, v[66:67]
	v_lshl_add_u64 v[76:77], v[68:69], 0, v[156:157]
	v_lshl_add_u64 v[66:67], s[66:67], 0, v[66:67]
	v_lshl_add_u64 v[66:67], v[66:67], 0, v[156:157]
	s_waitcnt vmcnt(18)
	v_pk_add_f32 v[56:57], v[56:57], v[210:211]
	s_waitcnt vmcnt(17)
	v_pk_add_f32 v[62:63], v[62:63], v[216:217]
	v_pk_add_f32 v[60:61], v[60:61], v[214:215]
	v_mul_f32_e32 v69, v63, v63
	v_mul_f32_e32 v68, v61, v61
	v_fmac_f32_e32 v68, v60, v60
	v_fmac_f32_e32 v69, v62, v62
	v_add_f32_e32 v68, v68, v69
	v_mul_f32_e32 v69, v57, v57
	v_pk_add_f32 v[58:59], v[58:59], v[212:213]
	v_fmac_f32_e32 v69, v56, v56
	v_add_f32_e32 v68, v68, v69
	v_mul_f32_e32 v69, v59, v59
	global_store_dwordx4 v[66:67], v[60:63], off
	global_store_dwordx4 v[66:67], v[56:59], off offset:16
	v_fmac_f32_e32 v69, v58, v58
	v_pk_mul_f32 v[60:61], v[52:53], v[60:61]
	v_add_f32_e32 v70, v69, v68
	v_pk_mul_f32 v[68:69], v[50:51], v[58:59]
	v_pk_mul_f32 v[58:59], v[48:49], v[56:57]
	v_cvt_pk_bf16_f32 v56, v60, v61
	v_lshlrev_b64 v[60:61], 12, v[64:65]
	v_lshl_add_u64 v[60:61], s[10:11], 0, v[60:61]
	v_pk_mul_f32 v[62:63], v[54:55], v[62:63]
	s_nop 0
	v_cvt_pk_bf16_f32 v57, v62, v63
	v_cvt_pk_bf16_f32 v58, v58, v59
	v_cvt_pk_bf16_f32 v59, v68, v69
	v_lshl_add_u64 v[68:69], v[154:155], 1, v[60:61]
	global_store_dwordx4 v[68:69], v[56:59], off
	s_nop 0
	s_waitcnt vmcnt(19)
	v_pk_add_f32 v[40:41], v[40:41], v[218:219]
	s_waitcnt vmcnt(18)
	v_pk_add_f32 v[46:47], v[46:47], v[224:225]
	v_pk_add_f32 v[44:45], v[44:45], v[222:223]
	v_mul_f32_e32 v57, v47, v47
	v_mul_f32_e32 v56, v45, v45
	v_fmac_f32_e32 v56, v44, v44
	v_fmac_f32_e32 v57, v46, v46
	v_add_f32_e32 v56, v56, v57
	v_mul_f32_e32 v57, v41, v41
	v_pk_add_f32 v[42:43], v[42:43], v[220:221]
	v_add_co_u32_e32 v200, vcc, 0x160000, v226
	s_nop 1
	v_addc_co_u32_e32 v201, vcc, 0, v227, vcc
	global_load_dwordx4 v[210:213], v[200:201], off offset:16
	global_load_dwordx4 v[214:217], v[200:201], off
	global_load_dwordx4 v[218:221], v[200:201], off offset:528
	global_load_dwordx4 v[222:225], v[200:201], off offset:512
	v_fmac_f32_e32 v57, v40, v40
	v_add_f32_e32 v56, v56, v57
	v_mul_f32_e32 v57, v43, v43
	v_fmac_f32_e32 v57, v42, v42
	v_add_f32_e32 v56, v57, v56
	global_store_dwordx4 v[66:67], v[44:47], off offset:512
	global_store_dwordx4 v[66:67], v[40:43], off offset:528
	v_add_f32_e32 v58, v70, v56
	v_pk_mul_f32 v[44:45], v[28:29], v[44:45]
	v_pk_mul_f32 v[56:57], v[26:27], v[42:43]
	v_pk_mul_f32 v[42:43], v[24:25], v[40:41]
	v_cvt_pk_bf16_f32 v40, v44, v45
	v_pk_mul_f32 v[46:47], v[30:31], v[46:47]
	s_nop 0
	v_cvt_pk_bf16_f32 v41, v46, v47
	v_cvt_pk_bf16_f32 v42, v42, v43
	v_cvt_pk_bf16_f32 v43, v56, v57
	global_store_dwordx4 v[68:69], v[40:43], off offset:256
	ds_swizzle_b32 v40, v58 offset:swizzle(SWAP,16)
	s_waitcnt lgkmcnt(0)
	v_add_f32_e32 v40, v58, v40
	v_mov_b32_e32 v41, v40
	s_nop 1
	v_permlane32_swap_b32_e32 v40, v41
	s_and_saveexec_b64 s[14:15], s[42:43]
	v_lshl_add_u64 v[42:43], v[64:65], 2, s[12:13]
	v_add_f32_e32 v40, v40, v41
	global_atomic_add_f32 v[42:43], v40, off
;     template <bool GATE> __device__ __forceinline__ void run(const f32x4 (&acc)[2][2][4][2], const Unit& u, int wr, int wc, int fr, int fq) const {
;     ...
;             for (int m = 0; m < 4; ++m) { const size_t r = (size_t)(row0 + ai * HALF + m * 16); float ss = 0.f;
; #pragma unroll
;                 for (int bj = 0; bj < 2; ++bj) { const int c = col0 + bj * HALF; f32x4 v0 = acc[ai][bj][m][0], v1 = acc[ai][bj][m][1];
;                     if (MODE == EP_INPROJ) { if (gate) { v0 = sigmoid4(v0 + bv[bj][0]); v1 = sigmoid4(v1 + bv[bj][1]); } }
;                     if (MODE == EP_T1 || MODE == EP_MERGE) { f32x4 g0, g1; unpack8(*(const u32x4*)(Gt + r * ldg + c), g0, g1); v0 = v0 * g0; v1 = v1 * g1; }
;                     if (MODE == EP_MERGE) { f32x4 t0, t1; unpack8(*(const u32x4*)(T + r * ldt + c), t0, t1); v0 = v0 + t0; v1 = v1 + t1; }
;                     if (MODE == EP_RELU2) {
; #pragma unroll
;                         for (int i = 0; i < 4; ++i) { const float a = fmaxf(v0[i], 0.f), b = fmaxf(v1[i], 0.f); v0[i] = a * a * rsc[ai][m]; v1[i] = b * b * rsc[ai][m]; } }
;                     if (MODE == EP_RESID_N) { const float* xp = X + r * 2048 + c; float* op = XO + r * 2048 + c;
;                         const f32x4 y0 = *(const f32x4*)xp + v0, y1 = *(const f32x4*)(xp + 4) + v1; *(f32x4*)op = y0; *(f32x4*)(op + 4) = y1;
;                         ss += (y0[0] * y0[0] + y0[1] * y0[1]) + (y0[2] * y0[2] + y0[3] * y0[3]) + (y1[0] * y1[0] + y1[1] * y1[1]) + (y1[2] * y1[2] + y1[3] * y1[3]);
;                         v0 = y0 * bv[bj][0]; v1 = y1 * bv[bj][1]; }
;                     if (MODE == EP_RESID) { const float* xp = X + r * 2048 + c; float* op = XO + r * 2048 + c;
;                         const f32x4 x0 = *(const f32x4*)xp, x1 = *(const f32x4*)(xp + 4); *(f32x4*)op = x0 + v0; *(f32x4*)(op + 4) = x1 + v1; }
;                     else { u32x4 w; w.x = cvt_pk_bf16(v0[0], v0[1]); w.y = cvt_pk_bf16(v0[2], v0[3]); w.z = cvt_pk_bf16(v1[0], v1[1]); w.w = cvt_pk_bf16(v1[2], v1[3]);
;                         *(u32x4*)(O + r * ldc + c) = w; } }
;                 if (MODE == EP_INPROJ) { if (u.pn >= ldt && u.pn < ldt + 8) {
; #pragma unroll
;                     for (int bj = 0; bj < 2; ++bj) { const f32x4 a = acc[ai][bj][m][0], b = acc[ai][bj][m][1];
.LBB0_699:
	s_or_b64 exec, exec, s[14:15]
	v_add_u32_e32 v40, 0xa0, v158
	v_ashrrev_i32_e32 v41, 31, v40
	v_lshlrev_b64 v[42:43], 13, v[40:41]
	v_lshl_add_u64 v[44:45], s[36:37], 0, v[42:43]
	v_lshl_add_u64 v[44:45], v[44:45], 0, v[156:157]
	v_lshl_add_u64 v[42:43], s[66:67], 0, v[42:43]
	v_lshl_add_u64 v[42:43], v[42:43], 0, v[156:157]
	s_waitcnt vmcnt(18)
	v_pk_add_f32 v[32:33], v[32:33], v[176:177]
	s_waitcnt vmcnt(17)
	v_pk_add_f32 v[38:39], v[38:39], v[182:183]
	v_pk_add_f32 v[36:37], v[36:37], v[180:181]
	v_mul_f32_e32 v47, v39, v39
	v_mul_f32_e32 v46, v37, v37
	v_fmac_f32_e32 v46, v36, v36
	v_fmac_f32_e32 v47, v38, v38
	v_add_f32_e32 v46, v46, v47
	v_mul_f32_e32 v47, v33, v33
	v_pk_add_f32 v[34:35], v[34:35], v[178:179]
	v_fmac_f32_e32 v47, v32, v32
	v_add_f32_e32 v46, v46, v47
	v_mul_f32_e32 v47, v35, v35
	global_store_dwordx4 v[42:43], v[36:39], off
	global_store_dwordx4 v[42:43], v[32:35], off offset:16
	v_fmac_f32_e32 v47, v34, v34
	v_pk_mul_f32 v[36:37], v[52:53], v[36:37]
	v_add_f32_e32 v56, v47, v46
	v_pk_mul_f32 v[46:47], v[50:51], v[34:35]
	v_pk_mul_f32 v[34:35], v[48:49], v[32:33]
	v_cvt_pk_bf16_f32 v32, v36, v37
	v_lshlrev_b64 v[36:37], 12, v[40:41]
	v_lshl_add_u64 v[36:37], s[10:11], 0, v[36:37]
	v_pk_mul_f32 v[38:39], v[54:55], v[38:39]
	s_nop 0
	v_cvt_pk_bf16_f32 v33, v38, v39
	v_cvt_pk_bf16_f32 v34, v34, v35
	v_cvt_pk_bf16_f32 v35, v46, v47
	v_lshl_add_u64 v[46:47], v[154:155], 1, v[36:37]
	global_store_dwordx4 v[46:47], v[32:35], off
	s_nop 0
	s_waitcnt vmcnt(19)
	v_pk_add_f32 v[16:17], v[16:17], v[184:185]
	s_waitcnt vmcnt(18)
	v_pk_add_f32 v[22:23], v[22:23], v[190:191]
	v_pk_add_f32 v[20:21], v[20:21], v[188:189]
	v_mul_f32_e32 v33, v23, v23
	v_mul_f32_e32 v32, v21, v21
	v_fmac_f32_e32 v32, v20, v20
	v_fmac_f32_e32 v33, v22, v22
	v_add_f32_e32 v32, v32, v33
	v_mul_f32_e32 v33, v17, v17
	v_pk_add_f32 v[18:19], v[18:19], v[186:187]
	v_fmac_f32_e32 v33, v16, v16
	v_add_f32_e32 v32, v32, v33
	v_mul_f32_e32 v33, v19, v19
	v_fmac_f32_e32 v33, v18, v18
	v_add_f32_e32 v32, v33, v32
	global_store_dwordx4 v[42:43], v[20:23], off offset:512
	global_store_dwordx4 v[42:43], v[16:19], off offset:528
	v_add_f32_e32 v34, v56, v32
	v_pk_mul_f32 v[20:21], v[28:29], v[20:21]
	v_pk_mul_f32 v[32:33], v[26:27], v[18:19]
	v_pk_mul_f32 v[18:19], v[24:25], v[16:17]
	v_cvt_pk_bf16_f32 v16, v20, v21
	v_pk_mul_f32 v[22:23], v[30:31], v[22:23]
	s_nop 0
	v_cvt_pk_bf16_f32 v17, v22, v23
	v_cvt_pk_bf16_f32 v18, v18, v19
	v_cvt_pk_bf16_f32 v19, v32, v33
	global_store_dwordx4 v[46:47], v[16:19], off offset:256
	ds_swizzle_b32 v16, v34 offset:swizzle(SWAP,16)
	s_waitcnt lgkmcnt(0)
	v_add_f32_e32 v16, v34, v16
	v_mov_b32_e32 v17, v16
	s_nop 1
	v_permlane32_swap_b32_e32 v16, v17
	s_and_saveexec_b64 s[14:15], s[42:43]
	v_lshl_add_u64 v[18:19], v[40:41], 2, s[12:13]
	v_add_f32_e32 v16, v16, v17
	global_atomic_add_f32 v[18:19], v16, off
.LBB0_701:
	s_or_b64 exec, exec, s[14:15]
	v_add_u32_e32 v16, 0xb0, v158
	v_ashrrev_i32_e32 v17, 31, v16
	v_lshlrev_b64 v[18:19], 13, v[16:17]
	v_lshl_add_u64 v[20:21], s[36:37], 0, v[18:19]
	v_lshl_add_u64 v[36:37], v[20:21], 0, v[156:157]
	v_lshl_add_u64 v[18:19], s[66:67], 0, v[18:19]
	v_lshl_add_u64 v[18:19], v[18:19], 0, v[156:157]
	s_waitcnt vmcnt(14)
	v_pk_add_f32 v[8:9], v[8:9], v[210:211]
	s_waitcnt vmcnt(13)
	v_pk_add_f32 v[14:15], v[14:15], v[216:217]
	v_pk_add_f32 v[12:13], v[12:13], v[214:215]
	v_mul_f32_e32 v21, v15, v15
	v_mul_f32_e32 v20, v13, v13
	v_fmac_f32_e32 v20, v12, v12
	v_fmac_f32_e32 v21, v14, v14
	v_add_f32_e32 v20, v20, v21
	v_mul_f32_e32 v21, v9, v9
	v_pk_add_f32 v[10:11], v[10:11], v[212:213]
	v_fmac_f32_e32 v21, v8, v8
	v_add_f32_e32 v20, v20, v21
	v_mul_f32_e32 v21, v11, v11
	global_store_dwordx4 v[18:19], v[12:15], off
	global_store_dwordx4 v[18:19], v[8:11], off offset:16
	v_fmac_f32_e32 v21, v10, v10
	v_pk_mul_f32 v[12:13], v[52:53], v[12:13]
	v_add_f32_e32 v22, v21, v20
	v_pk_mul_f32 v[20:21], v[50:51], v[10:11]
	v_pk_mul_f32 v[10:11], v[48:49], v[8:9]
	v_cvt_pk_bf16_f32 v8, v12, v13
	v_lshlrev_b64 v[12:13], 12, v[16:17]
	v_lshl_add_u64 v[12:13], s[10:11], 0, v[12:13]
	v_pk_mul_f32 v[14:15], v[54:55], v[14:15]
	s_nop 0
	v_cvt_pk_bf16_f32 v9, v14, v15
	v_cvt_pk_bf16_f32 v10, v10, v11
	v_cvt_pk_bf16_f32 v11, v20, v21
	v_lshl_add_u64 v[20:21], v[154:155], 1, v[12:13]
	global_store_dwordx4 v[20:21], v[8:11], off
	s_nop 0
	s_waitcnt vmcnt(15)
	v_pk_add_f32 v[0:1], v[0:1], v[218:219]
	s_waitcnt vmcnt(14)
	v_pk_add_f32 v[6:7], v[6:7], v[224:225]
	v_pk_add_f32 v[4:5], v[4:5], v[222:223]
	v_mul_f32_e32 v9, v7, v7
	v_mul_f32_e32 v8, v5, v5
	v_fmac_f32_e32 v8, v4, v4
	v_fmac_f32_e32 v9, v6, v6
	v_add_f32_e32 v8, v8, v9
	v_mul_f32_e32 v9, v1, v1
	v_pk_add_f32 v[2:3], v[2:3], v[220:221]
	v_fmac_f32_e32 v9, v0, v0
	v_add_f32_e32 v8, v8, v9
	v_mul_f32_e32 v9, v3, v3
	v_fmac_f32_e32 v9, v2, v2
	v_add_f32_e32 v8, v9, v8
	global_store_dwordx4 v[18:19], v[4:7], off offset:512
	global_store_dwordx4 v[18:19], v[0:3], off offset:528
	v_add_f32_e32 v10, v22, v8
	v_pk_mul_f32 v[4:5], v[28:29], v[4:5]
	v_pk_mul_f32 v[8:9], v[26:27], v[2:3]
	v_pk_mul_f32 v[2:3], v[24:25], v[0:1]
	v_cvt_pk_bf16_f32 v0, v4, v5
	v_pk_mul_f32 v[6:7], v[30:31], v[6:7]
	s_nop 0
	v_cvt_pk_bf16_f32 v1, v6, v7
	v_cvt_pk_bf16_f32 v2, v2, v3
	v_cvt_pk_bf16_f32 v3, v8, v9
	global_store_dwordx4 v[20:21], v[0:3], off offset:256
	ds_swizzle_b32 v0, v10 offset:swizzle(SWAP,16)
	s_waitcnt lgkmcnt(0)
	v_add_f32_e32 v0, v10, v0
	v_mov_b32_e32 v1, v0
	s_nop 1
	v_permlane32_swap_b32_e32 v0, v1
	s_and_saveexec_b64 s[14:15], s[42:43]
	v_lshl_add_u64 v[2:3], v[16:17], 2, s[12:13]
	v_add_f32_e32 v0, v0, v1
	global_atomic_add_f32 v[2:3], v0, off

;     template <bool GATE> __device__ __forceinline__ void run(const f32x4 (&acc)[2][2][4][2], const Unit& u, int wr, int wc, int fr, int fq) const {
;     ...
;         for (int ai = 0; ai < 2; ++ai)
; #pragma unroll
;             for (int m = 0; m < 4; ++m) { const size_t r = (size_t)(row0 + ai * HALF + m * 16); float ss = 0.f;
; #pragma unroll
;                 for (int bj = 0; bj < 2; ++bj) { const int c = col0 + bj * HALF; f32x4 v0 = acc[ai][bj][m][0], v1 = acc[ai][bj][m][1];
;                     if (MODE == EP_INPROJ) { if (gate) { v0 = sigmoid4(v0 + bv[bj][0]); v1 = sigmoid4(v1 + bv[bj][1]); } }
;                     if (MODE == EP_T1 || MODE == EP_MERGE) { f32x4 g0, g1; unpack8(*(const u32x4*)(Gt + r * ldg + c), g0, g1); v0 = v0 * g0; v1 = v1 * g1; }
;                     if (MODE == EP_MERGE) { f32x4 t0, t1; unpack8(*(const u32x4*)(T + r * ldt + c), t0, t1); v0 = v0 + t0; v1 = v1 + t1; }
;                     if (MODE == EP_RELU2) {
; #pragma unroll
;                         for (int i = 0; i < 4; ++i) { const float a = fmaxf(v0[i], 0.f), b = fmaxf(v1[i], 0.f); v0[i] = a * a * rsc[ai][m]; v1[i] = b * b * rsc[ai][m]; } }
;                     if (MODE == EP_RESID_N) { const float* xp = X + r * 2048 + c; float* op = XO + r * 2048 + c;
;                         const f32x4 y0 = *(const f32x4*)xp + v0, y1 = *(const f32x4*)(xp + 4) + v1; *(f32x4*)op = y0; *(f32x4*)(op + 4) = y1;
;                         ss += (y0[0] * y0[0] + y0[1] * y0[1]) + (y0[2] * y0[2] + y0[3] * y0[3]) + (y1[0] * y1[0] + y1[1] * y1[1]) + (y1[2] * y1[2] + y1[3] * y1[3]);
;                         v0 = y0 * bv[bj][0]; v1 = y1 * bv[bj][1]; }
;                     if (MODE == EP_RESID) { const float* xp = X + r * 2048 + c; float* op = XO + r * 2048 + c;
;                         const f32x4 x0 = *(const f32x4*)xp, x1 = *(const f32x4*)(xp + 4); *(f32x4*)op = x0 + v0; *(f32x4*)(op + 4) = x1 + v1; }
.LBB0_848:
	v_lshl_add_u32 v140, s63, 8, v144
	v_lshl_or_b32 v138, s62, 8, v146
	v_ashrrev_i32_e32 v141, 31, v140
	v_lshlrev_b64 v[142:143], 13, v[140:141]
	v_ashrrev_i32_e32 v139, 31, v138
	v_lshl_add_u64 v[200:201], s[66:67], 0, v[142:143]
	v_lshlrev_b64 v[142:143], 2, v[138:139]
	v_lshl_add_u64 v[138:139], v[200:201], 0, v[142:143]
	s_mov_b64 s[52:53], -1
	s_mov_b32 s25, 0
	global_load_dwordx4 v[148:151], v[138:139], off
	global_load_dwordx4 v[152:155], v[138:139], off offset:16
	global_load_dwordx4 v[156:159], v[138:139], off offset:512
	global_load_dwordx4 v[160:163], v[138:139], off offset:528
	s_mov_b32 s24, 0x20000
	v_lshl_add_u64 v[140:141], v[138:139], 0, s[24:25]
	global_load_dwordx4 v[164:167], v[140:141], off
	global_load_dwordx4 v[168:171], v[140:141], off offset:16
	global_load_dwordx4 v[172:175], v[140:141], off offset:512
	global_load_dwordx4 v[176:179], v[140:141], off offset:528
	s_mov_b32 s24, 0x40000
	v_lshl_add_u64 v[140:141], v[138:139], 0, s[24:25]
	global_load_dwordx4 v[180:183], v[140:141], off
	global_load_dwordx4 v[184:187], v[140:141], off offset:16
	global_load_dwordx4 v[188:191], v[140:141], off offset:512
	global_load_dwordx4 v[194:197], v[140:141], off offset:528
	s_mov_b32 s24, 0x60000
	v_lshl_add_u64 v[140:141], v[138:139], 0, s[24:25]
	global_load_dwordx4 v[210:213], v[140:141], off
	global_load_dwordx4 v[214:217], v[140:141], off offset:16
	global_load_dwordx4 v[218:221], v[140:141], off offset:512
	global_load_dwordx4 v[222:225], v[140:141], off offset:528
	s_waitcnt vmcnt(14)
	v_pk_add_f32 v[124:125], v[124:125], v[148:149]
	v_pk_add_f32 v[126:127], v[126:127], v[150:151]
	v_pk_add_f32 v[120:121], v[120:121], v[152:153]
	v_pk_add_f32 v[122:123], v[122:123], v[154:155]
	s_waitcnt vmcnt(12)
	v_pk_add_f32 v[116:117], v[116:117], v[156:157]
	v_pk_add_f32 v[118:119], v[118:119], v[158:159]
	v_pk_add_f32 v[112:113], v[112:113], v[160:161]
	v_pk_add_f32 v[114:115], v[114:115], v[162:163]
	global_store_dwordx4 v[138:139], v[124:127], off
	global_store_dwordx4 v[138:139], v[120:123], off offset:16
	global_store_dwordx4 v[138:139], v[116:119], off offset:512
	global_store_dwordx4 v[138:139], v[112:115], off offset:528
	s_mov_b32 s24, 0x100000
	v_lshl_add_u64 v[140:141], v[138:139], 0, s[24:25]
	global_load_dwordx4 v[148:151], v[140:141], off
	global_load_dwordx4 v[152:155], v[140:141], off offset:16
	global_load_dwordx4 v[156:159], v[140:141], off offset:512
	global_load_dwordx4 v[160:163], v[140:141], off offset:528
	s_mov_b32 s24, 0x20000
	v_lshl_add_u64 v[142:143], v[138:139], 0, s[24:25]
	s_waitcnt vmcnt(18)
	v_pk_add_f32 v[108:109], v[108:109], v[164:165]
	v_pk_add_f32 v[110:111], v[110:111], v[166:167]
	v_pk_add_f32 v[104:105], v[104:105], v[168:169]
	v_pk_add_f32 v[106:107], v[106:107], v[170:171]
	s_waitcnt vmcnt(16)
	v_pk_add_f32 v[100:101], v[100:101], v[172:173]
	v_pk_add_f32 v[102:103], v[102:103], v[174:175]
	v_pk_add_f32 v[96:97], v[96:97], v[176:177]
	v_pk_add_f32 v[98:99], v[98:99], v[178:179]
	global_store_dwordx4 v[142:143], v[108:111], off
	global_store_dwordx4 v[142:143], v[104:107], off offset:16
	global_store_dwordx4 v[142:143], v[100:103], off offset:512
	global_store_dwordx4 v[142:143], v[96:99], off offset:528
	s_mov_b32 s24, 0x120000
	v_lshl_add_u64 v[140:141], v[138:139], 0, s[24:25]
	global_load_dwordx4 v[164:167], v[140:141], off
	global_load_dwordx4 v[168:171], v[140:141], off offset:16
	global_load_dwordx4 v[172:175], v[140:141], off offset:512
	global_load_dwordx4 v[176:179], v[140:141], off offset:528
	s_mov_b32 s24, 0x40000
	v_lshl_add_u64 v[142:143], v[138:139], 0, s[24:25]
	s_waitcnt vmcnt(22)
	v_pk_add_f32 v[92:93], v[92:93], v[180:181]
	v_pk_add_f32 v[94:95], v[94:95], v[182:183]
	v_pk_add_f32 v[88:89], v[88:89], v[184:185]
	v_pk_add_f32 v[90:91], v[90:91], v[186:187]
	s_waitcnt vmcnt(20)
	v_pk_add_f32 v[84:85], v[84:85], v[188:189]
	v_pk_add_f32 v[86:87], v[86:87], v[190:191]
	v_pk_add_f32 v[80:81], v[80:81], v[194:195]
	v_pk_add_f32 v[82:83], v[82:83], v[196:197]
	global_store_dwordx4 v[142:143], v[92:95], off
	global_store_dwordx4 v[142:143], v[88:91], off offset:16
	global_store_dwordx4 v[142:143], v[84:87], off offset:512
	global_store_dwordx4 v[142:143], v[80:83], off offset:528
	s_mov_b32 s24, 0x140000
	v_lshl_add_u64 v[140:141], v[138:139], 0, s[24:25]
	global_load_dwordx4 v[180:183], v[140:141], off
	global_load_dwordx4 v[184:187], v[140:141], off offset:16
	global_load_dwordx4 v[188:191], v[140:141], off offset:512
	global_load_dwordx4 v[194:197], v[140:141], off offset:528
	s_mov_b32 s24, 0x60000
	v_lshl_add_u64 v[142:143], v[138:139], 0, s[24:25]
	s_waitcnt vmcnt(26)
;     template <bool GATE> __device__ __forceinline__ void run(const f32x4 (&acc)[2][2][4][2], const Unit& u, int wr, int wc, int fr, int fq) const {
;     ...
;         for (int ai = 0; ai < 2; ++ai)
; #pragma unroll
;             for (int m = 0; m < 4; ++m) { const size_t r = (size_t)(row0 + ai * HALF + m * 16); float ss = 0.f;
; #pragma unroll
;                 for (int bj = 0; bj < 2; ++bj) { const int c = col0 + bj * HALF; f32x4 v0 = acc[ai][bj][m][0], v1 = acc[ai][bj][m][1];
;                     if (MODE == EP_INPROJ) { if (gate) { v0 = sigmoid4(v0 + bv[bj][0]); v1 = sigmoid4(v1 + bv[bj][1]); } }
;                     if (MODE == EP_T1 || MODE == EP_MERGE) { f32x4 g0, g1; unpack8(*(const u32x4*)(Gt + r * ldg + c), g0, g1); v0 = v0 * g0; v1 = v1 * g1; }
;                     if (MODE == EP_MERGE) { f32x4 t0, t1; unpack8(*(const u32x4*)(T + r * ldt + c), t0, t1); v0 = v0 + t0; v1 = v1 + t1; }
;                     if (MODE == EP_RELU2) {
; #pragma unroll
;                         for (int i = 0; i < 4; ++i) { const float a = fmaxf(v0[i], 0.f), b = fmaxf(v1[i], 0.f); v0[i] = a * a * rsc[ai][m]; v1[i] = b * b * rsc[ai][m]; } }
;                     if (MODE == EP_RESID_N) { const float* xp = X + r * 2048 + c; float* op = XO + r * 2048 + c;
;                         const f32x4 y0 = *(const f32x4*)xp + v0, y1 = *(const f32x4*)(xp + 4) + v1; *(f32x4*)op = y0; *(f32x4*)(op + 4) = y1;
;                         ss += (y0[0] * y0[0] + y0[1] * y0[1]) + (y0[2] * y0[2] + y0[3] * y0[3]) + (y1[0] * y1[0] + y1[1] * y1[1]) + (y1[2] * y1[2] + y1[3] * y1[3]);
;                         v0 = y0 * bv[bj][0]; v1 = y1 * bv[bj][1]; }
;                     if (MODE == EP_RESID) { const float* xp = X + r * 2048 + c; float* op = XO + r * 2048 + c;
;                         const f32x4 x0 = *(const f32x4*)xp, x1 = *(const f32x4*)(xp + 4); *(f32x4*)op = x0 + v0; *(f32x4*)(op + 4) = x1 + v1; }
; template <class Epi, class Sched, bool ALIGN_EPI = false, bool SP2 = false>
; __device__ __forceinline__ void gemm_phase(PG8_LAS unsigned char* lds, const Gemm g, const Sched& S, const Epi& E) {
;     ...
;         if constexpr (ALIGN_EPI) { if (wr == 0) PG8_BAR; }
;         if constexpr (!Epi::AFTER_DRAIN) { E(acc, cur, wr, wc, fr, fq); S.done(cur); }
;         if (!has_next) break;
; #pragma unroll
;         for (int a = 0; a < 2; ++a)
; #pragma unroll
;             for (int b = 0; b < 2; ++b)
	v_pk_add_f32 v[76:77], v[76:77], v[210:211]
	v_pk_add_f32 v[78:79], v[78:79], v[212:213]
	v_pk_add_f32 v[72:73], v[72:73], v[214:215]
	v_pk_add_f32 v[74:75], v[74:75], v[216:217]
	s_waitcnt vmcnt(24)
	v_pk_add_f32 v[68:69], v[68:69], v[218:219]
	v_pk_add_f32 v[70:71], v[70:71], v[220:221]
	v_pk_add_f32 v[64:65], v[64:65], v[222:223]
	v_pk_add_f32 v[66:67], v[66:67], v[224:225]
	global_store_dwordx4 v[142:143], v[76:79], off
	global_store_dwordx4 v[142:143], v[72:75], off offset:16
	global_store_dwordx4 v[142:143], v[68:71], off offset:512
	global_store_dwordx4 v[142:143], v[64:67], off offset:528
	s_mov_b32 s24, 0x160000
	v_lshl_add_u64 v[140:141], v[138:139], 0, s[24:25]
	global_load_dwordx4 v[210:213], v[140:141], off
	global_load_dwordx4 v[214:217], v[140:141], off offset:16
	global_load_dwordx4 v[218:221], v[140:141], off offset:512
	global_load_dwordx4 v[222:225], v[140:141], off offset:528
	s_mov_b32 s24, 0x100000
	v_lshl_add_u64 v[142:143], v[138:139], 0, s[24:25]
	s_waitcnt vmcnt(26)
	v_pk_add_f32 v[60:61], v[60:61], v[148:149]
	v_pk_add_f32 v[62:63], v[62:63], v[150:151]
	v_pk_add_f32 v[56:57], v[56:57], v[152:153]
	v_pk_add_f32 v[58:59], v[58:59], v[154:155]
	s_waitcnt vmcnt(24)
	v_pk_add_f32 v[52:53], v[52:53], v[156:157]
	v_pk_add_f32 v[54:55], v[54:55], v[158:159]
	v_pk_add_f32 v[48:49], v[48:49], v[160:161]
	v_pk_add_f32 v[50:51], v[50:51], v[162:163]
	global_store_dwordx4 v[142:143], v[60:63], off
	global_store_dwordx4 v[142:143], v[56:59], off offset:16
	global_store_dwordx4 v[142:143], v[52:55], off offset:512
	global_store_dwordx4 v[142:143], v[48:51], off offset:528
	s_mov_b32 s24, 0x120000
	v_lshl_add_u64 v[142:143], v[138:139], 0, s[24:25]
	s_waitcnt vmcnt(22)
	v_pk_add_f32 v[44:45], v[44:45], v[164:165]
	v_pk_add_f32 v[46:47], v[46:47], v[166:167]
	v_pk_add_f32 v[40:41], v[40:41], v[168:169]
	v_pk_add_f32 v[42:43], v[42:43], v[170:171]
	s_waitcnt vmcnt(20)
	v_pk_add_f32 v[36:37], v[36:37], v[172:173]
	v_pk_add_f32 v[38:39], v[38:39], v[174:175]
	v_pk_add_f32 v[32:33], v[32:33], v[176:177]
	v_pk_add_f32 v[34:35], v[34:35], v[178:179]
	global_store_dwordx4 v[142:143], v[44:47], off
	global_store_dwordx4 v[142:143], v[40:43], off offset:16
	global_store_dwordx4 v[142:143], v[36:39], off offset:512
	global_store_dwordx4 v[142:143], v[32:35], off offset:528
	s_mov_b32 s24, 0x140000
	v_lshl_add_u64 v[142:143], v[138:139], 0, s[24:25]
	s_waitcnt vmcnt(18)
	v_pk_add_f32 v[28:29], v[28:29], v[180:181]
	v_pk_add_f32 v[30:31], v[30:31], v[182:183]
	v_pk_add_f32 v[24:25], v[24:25], v[184:185]
	v_pk_add_f32 v[26:27], v[26:27], v[186:187]
	s_waitcnt vmcnt(16)
	v_pk_add_f32 v[20:21], v[20:21], v[188:189]
	v_pk_add_f32 v[22:23], v[22:23], v[190:191]
	v_pk_add_f32 v[16:17], v[16:17], v[194:195]
	v_pk_add_f32 v[18:19], v[18:19], v[196:197]
	global_store_dwordx4 v[142:143], v[28:31], off
	global_store_dwordx4 v[142:143], v[24:27], off offset:16
	global_store_dwordx4 v[142:143], v[20:23], off offset:512
	global_store_dwordx4 v[142:143], v[16:19], off offset:528
	s_mov_b32 s24, 0x160000
	v_lshl_add_u64 v[142:143], v[138:139], 0, s[24:25]
	s_waitcnt vmcnt(14)
	v_pk_add_f32 v[12:13], v[12:13], v[210:211]
	v_pk_add_f32 v[14:15], v[14:15], v[212:213]
	v_pk_add_f32 v[8:9], v[8:9], v[214:215]
	v_pk_add_f32 v[10:11], v[10:11], v[216:217]
	s_waitcnt vmcnt(12)
	v_pk_add_f32 v[4:5], v[4:5], v[218:219]
	v_pk_add_f32 v[6:7], v[6:7], v[220:221]
	v_pk_add_f32 v[0:1], v[0:1], v[222:223]
	v_pk_add_f32 v[2:3], v[2:3], v[224:225]
	global_store_dwordx4 v[142:143], v[12:15], off
	global_store_dwordx4 v[142:143], v[8:11], off offset:16
	global_store_dwordx4 v[142:143], v[4:7], off offset:512
	global_store_dwordx4 v[142:143], v[0:3], off offset:528
	s_andn2_b64 vcc, exec, s[40:41]
	s_cbranch_vccnz .LBB0_837
	s_andn2_b64 vcc, exec, s[14:15]
	s_cbranch_vccnz .LBB0_836
	s_barrier
	s_branch .LBB0_836
